# k19: attention steady loops issue K/V LDS-DMA through an SGPR base + per-lane 32-bit offset (SALU pointer advance) instead of 64-bit VALU pointer adds
# speedup vs baseline: 1.0079x; 1.0079x over previous
.LBB0_1330:
	v_lshlrev_b32_e32 v49, 1, v48
	v_lshlrev_b32_e32 v48, 4, v48
	v_and_b32_e32 v235, 32, v49
	v_and_b32_e32 v48, 0xc0, v48
	v_lshl_or_b32 v233, v242, 8, v48
	v_add_u32_e32 v48, 0, v235
	v_add3_u32 v239, v48, v232, v233
	v_max3_f32 v48, v32, v33, v16
	v_max3_f32 v49, v34, v35, v17
	s_and_b32 s5, s5, 0x3fffffc0
	v_max3_f32 v48, v48, v18, v19
	v_max3_f32 v49, v49, v38, v39
	s_lshl_b32 s5, s5, 2
	v_max3_f32 v48, v48, v36, v37
	v_max3_f32 v49, v49, v22, v23
	s_add_i32 s6, s68, 0x100
	v_max3_f32 v48, v48, v20, v21
	v_max3_f32 v49, v49, v42, v43
	s_add_i32 s75, s5, 0
	v_max3_f32 v48, v48, v40, v41
	v_max3_f32 v49, v49, v26, v27
	s_add_i32 s75, s75, 0x12000
	v_max3_f32 v48, v48, v24, v25
	v_max3_f32 v49, v49, v46, v47
	s_lshr_b32 s67, s6, 6
	v_max3_f32 v48, v48, v44, v45
	v_max3_f32 v49, v49, v30, v31
	s_cmp_lg_u32 0, -1
	v_max3_f32 v48, v48, v28, v29
	s_mov_b32 s10, 1
	v_max_f32_e32 v48, v48, v49
	s_mov_b32 s38, 0
	v_mov_b32_e32 v49, v48
	s_nop 1
	v_permlane32_swap_b32_e32 v48, v49
	v_max_f32_e32 v48, v48, v49
	v_lshlrev_b32_e32 v240, 4, v242
	v_add_f32_e32 v237, v213, v48
	v_sub_f32_e32 v16, v16, v48
	v_sub_f32_e32 v17, v17, v48
	v_sub_f32_e32 v32, v32, v48
	v_sub_f32_e32 v33, v33, v48
	v_sub_f32_e32 v34, v34, v48
	s_nop 0
	v_xor_b32_e32 v64, 0x80000000, v237
	v_mov_b32_e32 v65, v64
	v_mov_b32_e32 v66, v64
	v_mov_b32_e32 v67, v64
	v_mov_b32_e32 v68, v64
	v_mov_b32_e32 v69, v64
	v_mov_b32_e32 v70, v64
	v_mov_b32_e32 v71, v64
	v_mov_b32_e32 v72, v64
	v_mov_b32_e32 v73, v64
	v_mov_b32_e32 v74, v64
	v_mov_b32_e32 v75, v64
	v_mov_b32_e32 v76, v64
	v_mov_b32_e32 v77, v64
	v_mov_b32_e32 v78, v64
	v_mov_b32_e32 v79, v64
	s_waitcnt vmcnt(0) lgkmcnt(0)
	s_barrier
	v_exp_f32_e32 v80, v16
	v_exp_f32_e32 v81, v17
	v_lshl_add_u64 v[16:17], v[214:215], 0, s[18:19]
	s_mov_b32 m0, s76
	s_nop 0
	global_load_lds_dwordx4 v[16:17], off
	s_cselect_b32 s5, 0, 0
	s_add_i32 s4, s5, s4
	v_lshl_add_u64 v[16:17], v[216:217], 0, s[14:15]
	s_add_i32 s5, s4, 0xa000
	s_mov_b32 m0, s5
	s_nop 0
	global_load_lds_dwordx4 v[16:17], off
	v_lshl_add_u64 v[16:17], v[216:217], 0, s[20:21]
	s_add_i32 s4, s4, 0xc000
	s_mov_b32 m0, s4
	s_nop 0
	global_load_lds_dwordx4 v[16:17], off
	ds_read_b128 v[204:207], v238 offset:8192
	ds_read_b128 v[200:203], v238 offset:8704
	ds_read_b128 v[196:199], v238 offset:10240
	ds_read_b128 v[192:195], v238 offset:10752
	ds_read_b128 v[188:191], v238 offset:12288
	ds_read_b128 v[184:187], v238 offset:12800
	ds_read_b128 v[180:183], v238 offset:14336
	ds_read_b128 v[176:179], v238 offset:14848
	v_sub_f32_e32 v18, v18, v48
	v_sub_f32_e32 v35, v35, v48
	v_sub_f32_e32 v19, v19, v48
	v_sub_f32_e32 v36, v36, v48
	v_sub_f32_e32 v20, v20, v48
	v_sub_f32_e32 v37, v37, v48
	v_sub_f32_e32 v21, v21, v48
	v_sub_f32_e32 v38, v38, v48
	v_sub_f32_e32 v22, v22, v48
	v_sub_f32_e32 v39, v39, v48
	v_sub_f32_e32 v23, v23, v48
	v_sub_f32_e32 v40, v40, v48
	v_sub_f32_e32 v24, v24, v48
	v_sub_f32_e32 v41, v41, v48
	v_sub_f32_e32 v25, v25, v48
	v_sub_f32_e32 v42, v42, v48
	v_sub_f32_e32 v26, v26, v48
	v_sub_f32_e32 v43, v43, v48
	v_sub_f32_e32 v27, v27, v48
	v_sub_f32_e32 v44, v44, v48
	v_sub_f32_e32 v28, v28, v48
	v_sub_f32_e32 v45, v45, v48
	v_sub_f32_e32 v29, v29, v48
	v_sub_f32_e32 v46, v46, v48
	v_sub_f32_e32 v30, v30, v48
	v_sub_f32_e32 v47, v47, v48
	v_sub_f32_e32 v31, v31, v48
	v_exp_f32_e32 v96, v32
	v_exp_f32_e32 v97, v33
	v_exp_f32_e32 v98, v34
	v_exp_f32_e32 v99, v35
	v_exp_f32_e32 v100, v36
	v_exp_f32_e32 v101, v37
	v_exp_f32_e32 v102, v38
	v_exp_f32_e32 v103, v39
	v_exp_f32_e32 v104, v40
	v_exp_f32_e32 v105, v41
	v_exp_f32_e32 v106, v42
	v_exp_f32_e32 v107, v43
	v_exp_f32_e32 v108, v44
	v_exp_f32_e32 v109, v45
	v_exp_f32_e32 v110, v46
	v_exp_f32_e32 v111, v47
	v_exp_f32_e32 v82, v18
	v_exp_f32_e32 v83, v19
	v_exp_f32_e32 v84, v20
	v_exp_f32_e32 v85, v21
	v_exp_f32_e32 v86, v22
	v_exp_f32_e32 v87, v23
	v_exp_f32_e32 v88, v24
	v_exp_f32_e32 v89, v25
	v_exp_f32_e32 v90, v26
	v_exp_f32_e32 v91, v27
	v_exp_f32_e32 v92, v28
	v_exp_f32_e32 v93, v29
	v_exp_f32_e32 v94, v30
	v_exp_f32_e32 v95, v31
	s_waitcnt vmcnt(3) lgkmcnt(0)
	s_barrier
	v_cndmask_b32_e64 v16, 0, 1, s[8:9]
	s_add_i32 s70, s67, -5
	v_cmp_ne_u32_e64 s[6:7], 1, v16
	s_andn2_b64 vcc, exec, s[8:9]
	v_cmp_gt_u32_e64 s[8:9], 32, v231
	v_lshl_add_u32 v234, v230, 2, s75
	s_cbranch_vccnz .LBB0_1346
	v_mov_b64_e32 v[62:63], v[14:15]
	v_mov_b64_e32 v[46:47], v[14:15]
	v_mov_b64_e32 v[30:31], v[14:15]
	v_lshl_add_u64 v[220:221], v[218:219], 0, s[18:19]
	v_lshl_add_u64 v[222:223], v[216:217], 0, s[18:19]
	v_lshl_add_u64 v[224:225], v[214:215], 0, s[22:23]
	s_nop 0
	v_readfirstlane_b32 s98, v224
	v_readfirstlane_b32 s99, v225
	v_readfirstlane_b32 s100, v222
	v_readfirstlane_b32 s101, v223
	s_nop 1
	v_subrev_u32_e32 v248, s98, v224
	v_subrev_u32_e32 v250, s100, v222
	s_add_u32 s98, s98, s24
	s_addc_u32 s99, s99, s25
	s_add_u32 s100, s100, s24
	s_addc_u32 s101, s101, s25
	v_add_u32_e32 v249, 0x20000, v248
	v_add_u32_e32 v251, 0x20000, v250
	v_add_u32_e32 v252, 0x80, v250
	v_add_u32_e32 v253, 0x80, v251
	s_movk_i32 s38, 0x4000
	s_movk_i32 s11, 0x2000
	s_mov_b32 s4, 0
	v_mov_b32_e32 v241, 0
	v_mov_b64_e32 v[60:61], v[12:13]
	v_mov_b64_e32 v[58:59], v[10:11]
	v_mov_b64_e32 v[56:57], v[8:9]
	v_mov_b64_e32 v[54:55], v[6:7]
	v_mov_b64_e32 v[52:53], v[4:5]
	v_mov_b64_e32 v[50:51], v[2:3]
	v_mov_b64_e32 v[48:49], v[0:1]
	v_mov_b64_e32 v[44:45], v[12:13]
	v_mov_b64_e32 v[42:43], v[10:11]
	v_mov_b64_e32 v[40:41], v[8:9]
	v_mov_b64_e32 v[38:39], v[6:7]
	v_mov_b64_e32 v[36:37], v[4:5]
	v_mov_b64_e32 v[34:35], v[2:3]
	v_mov_b64_e32 v[32:33], v[0:1]
	v_mov_b64_e32 v[28:29], v[12:13]
	v_mov_b64_e32 v[26:27], v[10:11]
	v_mov_b64_e32 v[24:25], v[8:9]
	v_mov_b64_e32 v[22:23], v[6:7]
	v_mov_b64_e32 v[20:21], v[4:5]
	v_mov_b64_e32 v[18:19], v[2:3]
	v_mov_b64_e32 v[16:17], v[0:1]
.LBB0_1332:
	s_lshl_b32 s4, s4, 1
	v_add_u32_e32 v243, s4, v239
	ds_read_b64_tr_b16 v[208:209], v243 offset:24576
	ds_read_b64_tr_b16 v[210:211], v243 offset:25088
	s_waitcnt lgkmcnt(9)
	v_mfma_f32_32x32x16_bf16 v[128:143], v[204:207], v[172:175], v[64:79]
	v_add_f32_e32 v112, v96, v97
	v_add_f32_e32 v112, v98, v112
	v_add_f32_e32 v112, v99, v112
	v_add_f32_e32 v112, v100, v112
	v_add_f32_e32 v112, v101, v112
	v_cvt_pk_bf16_f32 v164, v96, v97
	v_cvt_pk_bf16_f32 v165, v98, v99
	ds_read_b64_tr_b16 v[96:97], v243 offset:28672
	ds_read_b64_tr_b16 v[98:99], v243 offset:29184
	v_add_f32_e32 v112, v102, v112
	v_add_f32_e32 v112, v103, v112
	v_add_f32_e32 v112, v104, v112
	v_add_f32_e32 v144, v105, v112
	s_waitcnt lgkmcnt(10)
	v_mfma_f32_32x32x16_bf16 v[112:127], v[200:203], v[172:175], v[64:79]
	v_cvt_pk_bf16_f32 v166, v100, v101
	v_cvt_pk_bf16_f32 v167, v102, v103
	ds_read_b64_tr_b16 v[100:101], v243 offset:25600
	ds_read_b64_tr_b16 v[102:103], v243 offset:26112
	s_waitcnt lgkmcnt(11)
	v_mfma_f32_32x32x16_bf16 v[128:143], v[196:199], v[168:171], v[128:143]
	v_add_f32_e32 v144, v106, v144
	v_add_f32_e32 v144, v107, v144
	v_add_f32_e32 v144, v108, v144
	v_add_f32_e32 v144, v109, v144
	v_cvt_pk_bf16_f32 v156, v104, v105
	v_cvt_pk_bf16_f32 v157, v106, v107
	ds_read_b64_tr_b16 v[104:105], v243 offset:29696
	ds_read_b64_tr_b16 v[106:107], v243 offset:30208
	s_waitcnt lgkmcnt(12)
	v_mfma_f32_32x32x16_bf16 v[112:127], v[192:195], v[168:171], v[112:127]
	v_add_f32_e32 v144, v110, v144
	v_add_f32_e32 v144, v111, v144
	v_add_f32_e32 v144, v80, v144
	v_add_f32_e32 v144, v81, v144
	v_cvt_pk_bf16_f32 v158, v108, v109
	v_cvt_pk_bf16_f32 v159, v110, v111
	ds_read_b64_tr_b16 v[108:109], v243 offset:26624
	ds_read_b64_tr_b16 v[110:111], v243 offset:27136
	s_waitcnt lgkmcnt(13)
	v_mfma_f32_32x32x16_bf16 v[128:143], v[188:191], v[160:163], v[128:143]
	v_add_f32_e32 v144, v82, v144
	v_add_f32_e32 v144, v83, v144
	v_add_f32_e32 v144, v84, v144
	v_add_f32_e32 v144, v85, v144
	v_cvt_pk_bf16_f32 v148, v80, v81
	v_cvt_pk_bf16_f32 v149, v82, v83
	ds_read_b64_tr_b16 v[80:81], v243 offset:30720
	ds_read_b64_tr_b16 v[82:83], v243 offset:31232
	s_waitcnt lgkmcnt(14)
	v_mfma_f32_32x32x16_bf16 v[112:127], v[184:187], v[160:163], v[112:127]
	v_add_f32_e32 v144, v86, v144
	v_add_f32_e32 v144, v87, v144
	v_add_f32_e32 v144, v88, v144
	v_add_f32_e32 v144, v89, v144
	v_cvt_pk_bf16_f32 v150, v84, v85
	v_cvt_pk_bf16_f32 v151, v86, v87
	ds_read_b64_tr_b16 v[84:85], v243 offset:27648
	ds_read_b64_tr_b16 v[86:87], v243 offset:28160
	s_waitcnt lgkmcnt(14)
	v_mfma_f32_32x32x16_bf16 v[128:143], v[180:183], v[152:155], v[128:143]
	v_add_f32_e32 v144, v90, v144
	v_add_f32_e32 v144, v91, v144
	v_add_f32_e32 v144, v92, v144
	v_add_f32_e32 v184, v93, v144
	v_cvt_pk_bf16_f32 v144, v88, v89
	v_cvt_pk_bf16_f32 v145, v90, v91
	ds_read_b64_tr_b16 v[88:89], v243 offset:31744
	ds_read_b64_tr_b16 v[90:91], v243 offset:32256
	v_mfma_f32_32x32x16_bf16 v[112:127], v[176:179], v[152:155], v[112:127]
	v_add_f32_e32 v146, v94, v184
	v_add_f32_e32 v146, v95, v146
	v_add_f32_e32 v180, 0, v146
	v_cvt_pk_bf16_f32 v146, v92, v93
	v_cvt_pk_bf16_f32 v147, v94, v95
	s_add_i32 s4, s11, s76
	s_mov_b32 m0, s4
	s_nop 0
	global_load_lds_dwordx4 v248, s[98:99]
	s_lshl_b32 s4, s38, 1
	s_add_i32 s4, s4, s77
	s_mov_b32 m0, s4
	s_nop 0
	global_load_lds_dwordx4 v250, s[100:101]
	s_addk_i32 s4, 0x2000
	s_mov_b32 m0, s4
	s_nop 0
	global_load_lds_dwordx4 v252, s[100:101]
	v_max_f32_e32 v92, v128, v129
	v_max3_f32 v93, v130, v131, v113
	v_max3_f32 v92, v92, v112, v114
	v_max3_f32 v92, v92, v115, v132
	v_max3_f32 v93, v93, v134, v135
	v_max3_f32 v92, v92, v133, v116
	v_max3_f32 v93, v93, v118, v119
	v_max3_f32 v92, v92, v117, v136
	v_max3_f32 v93, v93, v138, v139
	v_max3_f32 v92, v92, v137, v120
	v_max3_f32 v93, v93, v122, v123
	v_max3_f32 v92, v92, v121, v140
	v_max3_f32 v93, v93, v142, v143
	v_max3_f32 v92, v92, v141, v124
	v_max3_f32 v93, v93, v126, v127
	v_max3_f32 v92, v92, v125, v93
	v_mov_b32_e32 v93, v92
	s_nop 1
	v_permlane32_swap_b32_e32 v92, v93
	v_max_f32_e32 v92, v92, v93
	v_cmp_lt_f32_e32 vcc, s41, v92
	s_cmp_lg_u64 vcc, 0
	v_add_f32_e32 v241, v241, v180
	s_cselect_b64 s[36:37], -1, 0
	s_cbranch_vccnz .LBB0_1340

.LBB0_1335:
	s_add_i32 s4, s38, 0x2000
	s_cmpk_lg_i32 s38, 0x4000
	s_cselect_b32 s78, s4, 0
	s_lshl_b32 s4, s11, 1
	v_add_u32_e32 v209, s4, v239
	ds_read_b64_tr_b16 v[196:197], v209 offset:24576
	ds_read_b64_tr_b16 v[198:199], v209 offset:25088
	s_waitcnt lgkmcnt(9)
	v_mfma_f32_32x32x16_bf16 v[96:111], v[80:83], v[172:175], v[64:79]
	v_add_f32_e32 v84, v128, v129
	v_add_f32_e32 v84, v130, v84
	v_add_f32_e32 v84, v131, v84
	v_add_f32_e32 v84, v132, v84
	v_add_f32_e32 v84, v133, v84
	v_cvt_pk_bf16_f32 v164, v128, v129
	v_cvt_pk_bf16_f32 v165, v130, v131
	ds_read_b64_tr_b16 v[128:129], v209 offset:28672
	ds_read_b64_tr_b16 v[130:131], v209 offset:29184
	v_add_f32_e32 v80, v134, v84
	v_add_f32_e32 v80, v135, v80
	v_add_f32_e32 v80, v136, v80
	v_add_f32_e32 v144, v137, v80
	s_waitcnt lgkmcnt(10)
	v_mfma_f32_32x32x16_bf16 v[80:95], v[204:207], v[172:175], v[64:79]
	v_cvt_pk_bf16_f32 v166, v132, v133
	v_cvt_pk_bf16_f32 v167, v134, v135
	ds_read_b64_tr_b16 v[132:133], v209 offset:25600
	ds_read_b64_tr_b16 v[134:135], v209 offset:26112
	s_waitcnt lgkmcnt(11)
	v_mfma_f32_32x32x16_bf16 v[96:111], v[200:203], v[168:171], v[96:111]
	v_add_f32_e32 v144, v138, v144
	v_add_f32_e32 v144, v139, v144
	v_add_f32_e32 v144, v140, v144
	v_add_f32_e32 v144, v141, v144
	v_cvt_pk_bf16_f32 v156, v136, v137
	v_cvt_pk_bf16_f32 v157, v138, v139
	ds_read_b64_tr_b16 v[136:137], v209 offset:29696
	ds_read_b64_tr_b16 v[138:139], v209 offset:30208
	s_waitcnt lgkmcnt(12)
	v_mfma_f32_32x32x16_bf16 v[80:95], v[192:195], v[168:171], v[80:95]
	v_add_f32_e32 v144, v142, v144
	v_add_f32_e32 v144, v143, v144
	v_add_f32_e32 v144, v112, v144
	v_add_f32_e32 v144, v113, v144
	v_cvt_pk_bf16_f32 v158, v140, v141
	v_cvt_pk_bf16_f32 v159, v142, v143
	ds_read_b64_tr_b16 v[140:141], v209 offset:26624
	ds_read_b64_tr_b16 v[142:143], v209 offset:27136
	s_waitcnt lgkmcnt(13)
	v_mfma_f32_32x32x16_bf16 v[96:111], v[188:191], v[160:163], v[96:111]
	v_add_f32_e32 v144, v114, v144
	v_add_f32_e32 v144, v115, v144
	v_add_f32_e32 v144, v116, v144
	v_add_f32_e32 v144, v117, v144
	v_cvt_pk_bf16_f32 v148, v112, v113
	v_cvt_pk_bf16_f32 v149, v114, v115
	ds_read_b64_tr_b16 v[112:113], v209 offset:30720
	ds_read_b64_tr_b16 v[114:115], v209 offset:31232
	s_waitcnt lgkmcnt(14)
	v_mfma_f32_32x32x16_bf16 v[80:95], v[184:187], v[160:163], v[80:95]
	v_add_f32_e32 v144, v118, v144
	v_add_f32_e32 v144, v119, v144
	v_add_f32_e32 v144, v120, v144
	v_add_f32_e32 v144, v121, v144
	v_cvt_pk_bf16_f32 v150, v116, v117
	v_cvt_pk_bf16_f32 v151, v118, v119
	ds_read_b64_tr_b16 v[116:117], v209 offset:27648
	ds_read_b64_tr_b16 v[118:119], v209 offset:28160
	s_waitcnt lgkmcnt(14)
	v_mfma_f32_32x32x16_bf16 v[96:111], v[180:183], v[152:155], v[96:111]
	v_add_f32_e32 v144, v122, v144
	v_add_f32_e32 v144, v123, v144
	v_add_f32_e32 v144, v124, v144
	v_add_f32_e32 v184, v125, v144
	v_cvt_pk_bf16_f32 v144, v120, v121
	v_cvt_pk_bf16_f32 v145, v122, v123
	ds_read_b64_tr_b16 v[120:121], v209 offset:31744
	ds_read_b64_tr_b16 v[122:123], v209 offset:32256
	v_mfma_f32_32x32x16_bf16 v[80:95], v[176:179], v[152:155], v[80:95]
	v_add_f32_e32 v146, v126, v184
	v_add_f32_e32 v146, v127, v146
	v_add_f32_e32 v180, 0, v146
	v_cvt_pk_bf16_f32 v146, v124, v125
	v_cvt_pk_bf16_f32 v147, v126, v127
	v_max_f32_e32 v124, v96, v97
	s_nop 3
	s_nop 1
	v_max3_f32 v125, v98, v99, v81
	v_max3_f32 v124, v124, v80, v82
	v_max3_f32 v124, v124, v83, v100
	v_max3_f32 v125, v125, v102, v103
	v_max3_f32 v124, v124, v101, v84
	v_max3_f32 v125, v125, v86, v87
	v_max3_f32 v124, v124, v85, v104
	v_max3_f32 v125, v125, v106, v107
	v_max3_f32 v124, v124, v105, v88
	v_max3_f32 v125, v125, v90, v91
	v_max3_f32 v124, v124, v89, v108
	v_max3_f32 v125, v125, v110, v111
	v_max3_f32 v124, v124, v109, v92
	v_max3_f32 v125, v125, v94, v95
	v_max3_f32 v124, v124, v93, v125
	v_mov_b32_e32 v125, v124
	s_add_i32 s4, s38, s76
	s_nop 0
	v_permlane32_swap_b32_e32 v124, v125
	s_mov_b32 m0, s4
	s_nop 0
	global_load_lds_dwordx4 v249, s[98:99]
	s_lshl_b32 s4, s78, 1
	s_add_i32 s4, s4, s77
	s_mov_b32 m0, s4
	s_nop 0
	global_load_lds_dwordx4 v251, s[100:101]
	v_max_f32_e32 v124, v124, v125
	s_addk_i32 s4, 0x2000
	s_mov_b32 m0, s4
	s_nop 0
	global_load_lds_dwordx4 v253, s[100:101]
	v_cmp_lt_f32_e32 vcc, s41, v124
	s_cmp_lg_u64 vcc, 0
	v_add_f32_e32 v241, v241, v180
	s_cselect_b64 s[36:37], -1, 0
	s_cbranch_vccnz .LBB0_1343

.LBB0_1338:
	s_add_i32 s10, s10, 2
	s_add_i32 s4, s78, 0x2000
	s_cmpk_lg_i32 s78, 0x4000
	s_cselect_b32 s79, s4, 0
	s_add_u32 s98, s98, s16
	s_addc_u32 s99, s99, s17
	s_add_u32 s100, s100, s16
	s_addc_u32 s101, s101, s17
	s_cmp_ge_i32 s10, s70
	s_cbranch_scc1 .LBB0_1347
	s_mov_b32 s4, s38
	s_mov_b32 s11, s78
	s_mov_b32 s38, s79
	s_branch .LBB0_1332

.LBB0_1357:
	v_lshlrev_b32_e32 v48, 1, v231
	v_and_b32_e32 v234, 32, v48
	v_lshlrev_b32_e32 v48, 4, v241
	v_and_b32_e32 v48, 0xc0, v48
	v_add_u32_e32 v49, 0, v234
	v_lshl_or_b32 v235, v244, 8, v48
	v_max3_f32 v48, v32, v33, v16
	v_add3_u32 v240, v49, v232, v235
	v_max3_f32 v49, v34, v35, v17
	v_max3_f32 v48, v48, v18, v19
	s_and_b32 s5, s5, 0x3fffffc0
	v_max3_f32 v48, v48, v36, v37
	v_max3_f32 v49, v49, v38, v39
	s_lshl_b32 s5, s5, 2
	v_max3_f32 v48, v48, v20, v21
	v_max3_f32 v49, v49, v22, v23
	s_add_i32 s49, s5, 0
	v_max3_f32 v48, v48, v40, v41
	v_max3_f32 v49, v49, v42, v43
	s_add_i32 s49, s49, 0x12000
	v_max3_f32 v48, v48, v24, v25
	v_max3_f32 v49, v49, v26, v27
	s_cmp_lg_u32 0, -1
	v_max3_f32 v48, v48, v44, v45
	v_max3_f32 v49, v49, v46, v47
	s_mov_b32 s34, 1
	v_max3_f32 v48, v48, v28, v29
	v_max3_f32 v49, v49, v30, v31
	s_mov_b32 s36, 0
	v_max_f32_e32 v48, v48, v49
	v_lshlrev_b32_e32 v242, 4, v244
	v_mov_b32_e32 v49, v48
	s_nop 1
	v_permlane32_swap_b32_e32 v48, v49
	v_max_f32_e32 v48, v48, v49
	v_lshl_add_u32 v236, v230, 2, s49
	v_add_f32_e32 v238, v213, v48
	v_sub_f32_e32 v16, v16, v48
	v_sub_f32_e32 v17, v17, v48
	v_sub_f32_e32 v32, v32, v48
	v_sub_f32_e32 v33, v33, v48
	v_sub_f32_e32 v34, v34, v48
	s_nop 0
	v_xor_b32_e32 v64, 0x80000000, v238
	v_mov_b32_e32 v65, v64
	v_mov_b32_e32 v66, v64
	v_mov_b32_e32 v67, v64
	v_mov_b32_e32 v68, v64
	v_mov_b32_e32 v69, v64
	v_mov_b32_e32 v70, v64
	v_mov_b32_e32 v71, v64
	v_mov_b32_e32 v72, v64
	v_mov_b32_e32 v73, v64
	v_mov_b32_e32 v74, v64
	v_mov_b32_e32 v75, v64
	v_mov_b32_e32 v76, v64
	v_mov_b32_e32 v77, v64
	v_mov_b32_e32 v78, v64
	v_mov_b32_e32 v79, v64
	s_waitcnt vmcnt(0) lgkmcnt(0)
	s_barrier
	v_exp_f32_e32 v80, v16
	v_exp_f32_e32 v81, v17
	v_lshl_add_u64 v[16:17], v[214:215], 0, s[18:19]
	s_mov_b32 m0, s71
	s_nop 0
	global_load_lds_dwordx4 v[16:17], off
	s_cselect_b32 s5, 0, 0
	s_add_i32 s4, s5, s4
	v_lshl_add_u64 v[16:17], v[216:217], 0, s[14:15]
	s_add_i32 s5, s4, 0xa000
	s_mov_b32 m0, s5
	s_nop 0
	global_load_lds_dwordx4 v[16:17], off
	v_lshl_add_u64 v[16:17], v[216:217], 0, s[20:21]
	s_add_i32 s4, s4, 0xc000
	s_mov_b32 m0, s4
	s_nop 0
	global_load_lds_dwordx4 v[16:17], off
	ds_read_b128 v[204:207], v239 offset:8192
	ds_read_b128 v[200:203], v239 offset:8704
	ds_read_b128 v[196:199], v239 offset:10240
	ds_read_b128 v[192:195], v239 offset:10752
	ds_read_b128 v[188:191], v239 offset:12288
	ds_read_b128 v[184:187], v239 offset:12800
	ds_read_b128 v[180:183], v239 offset:14336
	ds_read_b128 v[176:179], v239 offset:14848
	v_sub_f32_e32 v18, v18, v48
	v_sub_f32_e32 v35, v35, v48
	v_sub_f32_e32 v19, v19, v48
	v_sub_f32_e32 v36, v36, v48
	v_sub_f32_e32 v20, v20, v48
	v_sub_f32_e32 v37, v37, v48
	v_sub_f32_e32 v21, v21, v48
	v_sub_f32_e32 v38, v38, v48
	v_sub_f32_e32 v22, v22, v48
	v_sub_f32_e32 v39, v39, v48
	v_sub_f32_e32 v23, v23, v48
	v_sub_f32_e32 v40, v40, v48
	v_sub_f32_e32 v24, v24, v48
	v_sub_f32_e32 v41, v41, v48
	v_sub_f32_e32 v25, v25, v48
	v_sub_f32_e32 v42, v42, v48
	v_sub_f32_e32 v26, v26, v48
	v_sub_f32_e32 v43, v43, v48
	v_sub_f32_e32 v27, v27, v48
	v_sub_f32_e32 v44, v44, v48
	v_sub_f32_e32 v28, v28, v48
	v_sub_f32_e32 v45, v45, v48
	v_sub_f32_e32 v29, v29, v48
	v_sub_f32_e32 v46, v46, v48
	v_sub_f32_e32 v30, v30, v48
	v_sub_f32_e32 v47, v47, v48
	v_sub_f32_e32 v31, v31, v48
	v_exp_f32_e32 v96, v32
	v_exp_f32_e32 v97, v33
	v_exp_f32_e32 v98, v34
	v_exp_f32_e32 v99, v35
	v_exp_f32_e32 v100, v36
	v_exp_f32_e32 v101, v37
	v_exp_f32_e32 v102, v38
	v_exp_f32_e32 v103, v39
	v_exp_f32_e32 v104, v40
	v_exp_f32_e32 v105, v41
	v_exp_f32_e32 v106, v42
	v_exp_f32_e32 v107, v43
	v_exp_f32_e32 v108, v44
	v_exp_f32_e32 v109, v45
	v_exp_f32_e32 v110, v46
	v_exp_f32_e32 v111, v47
	v_exp_f32_e32 v82, v18
	v_exp_f32_e32 v83, v19
	v_exp_f32_e32 v84, v20
	v_exp_f32_e32 v85, v21
	v_exp_f32_e32 v86, v22
	v_exp_f32_e32 v87, v23
	v_exp_f32_e32 v88, v24
	v_exp_f32_e32 v89, v25
	v_exp_f32_e32 v90, v26
	v_exp_f32_e32 v91, v27
	v_exp_f32_e32 v92, v28
	v_exp_f32_e32 v93, v29
	v_exp_f32_e32 v94, v30
	v_exp_f32_e32 v95, v31
	s_waitcnt vmcnt(3) lgkmcnt(0)
	s_barrier
	s_and_b64 vcc, exec, s[6:7]
	v_cmp_gt_u32_e64 s[6:7], 32, v231
	s_cbranch_vccnz .LBB0_1423
	v_mov_b64_e32 v[62:63], v[14:15]
	v_mov_b64_e32 v[46:47], v[14:15]
	v_mov_b64_e32 v[30:31], v[14:15]
	v_lshl_add_u64 v[220:221], v[218:219], 0, s[18:19]
	v_lshl_add_u64 v[222:223], v[216:217], 0, s[18:19]
	v_lshl_add_u64 v[224:225], v[214:215], 0, s[22:23]
	s_nop 0
	v_readfirstlane_b32 s98, v224
	v_readfirstlane_b32 s99, v225
	v_readfirstlane_b32 s100, v222
	v_readfirstlane_b32 s101, v223
	s_nop 1
	v_subrev_u32_e32 v248, s98, v224
	v_subrev_u32_e32 v250, s100, v222
	s_add_u32 s98, s98, s24
	s_addc_u32 s99, s99, s25
	s_add_u32 s100, s100, s24
	s_addc_u32 s101, s101, s25
	v_add_u32_e32 v249, 0x20000, v248
	v_add_u32_e32 v251, 0x20000, v250
	v_add_u32_e32 v252, 0x80, v250
	v_add_u32_e32 v253, 0x80, v251
	s_movk_i32 s36, 0x4000
	s_movk_i32 s35, 0x2000
	s_mov_b32 s4, 0
	v_mov_b32_e32 v243, 0
	v_mov_b64_e32 v[60:61], v[12:13]
	v_mov_b64_e32 v[58:59], v[10:11]
	v_mov_b64_e32 v[56:57], v[8:9]
	v_mov_b64_e32 v[54:55], v[6:7]
	v_mov_b64_e32 v[52:53], v[4:5]
	v_mov_b64_e32 v[50:51], v[2:3]
	v_mov_b64_e32 v[48:49], v[0:1]
	v_mov_b64_e32 v[44:45], v[12:13]
	v_mov_b64_e32 v[42:43], v[10:11]
	v_mov_b64_e32 v[40:41], v[8:9]
	v_mov_b64_e32 v[38:39], v[6:7]
	v_mov_b64_e32 v[36:37], v[4:5]
	v_mov_b64_e32 v[34:35], v[2:3]
	v_mov_b64_e32 v[32:33], v[0:1]
	v_mov_b64_e32 v[28:29], v[12:13]
	v_mov_b64_e32 v[26:27], v[10:11]
	v_mov_b64_e32 v[24:25], v[8:9]
	v_mov_b64_e32 v[22:23], v[6:7]
	v_mov_b64_e32 v[20:21], v[4:5]
	v_mov_b64_e32 v[18:19], v[2:3]
	v_mov_b64_e32 v[16:17], v[0:1]
.LBB0_1359:
	s_lshl_b32 s4, s4, 1
	v_add_u32_e32 v245, s4, v240
	ds_read_b64_tr_b16 v[208:209], v245 offset:24576
	ds_read_b64_tr_b16 v[210:211], v245 offset:25088
	s_waitcnt lgkmcnt(9)
	v_mfma_f32_32x32x16_bf16 v[128:143], v[204:207], v[172:175], v[64:79]
	v_add_f32_e32 v112, v96, v97
	v_add_f32_e32 v112, v98, v112
	v_add_f32_e32 v112, v99, v112
	v_add_f32_e32 v112, v100, v112
	v_add_f32_e32 v112, v101, v112
	v_cvt_pk_bf16_f32 v160, v96, v97
	v_cvt_pk_bf16_f32 v161, v98, v99
	ds_read_b64_tr_b16 v[96:97], v245 offset:28672
	ds_read_b64_tr_b16 v[98:99], v245 offset:29184
	v_add_f32_e32 v112, v102, v112
	v_add_f32_e32 v112, v103, v112
	v_add_f32_e32 v112, v104, v112
	v_add_f32_e32 v144, v105, v112
	s_waitcnt lgkmcnt(10)
	v_mfma_f32_32x32x16_bf16 v[112:127], v[200:203], v[172:175], v[64:79]
	v_cvt_pk_bf16_f32 v162, v100, v101
	v_cvt_pk_bf16_f32 v163, v102, v103
	ds_read_b64_tr_b16 v[100:101], v245 offset:25600
	ds_read_b64_tr_b16 v[102:103], v245 offset:26112
	s_waitcnt lgkmcnt(11)
	v_mfma_f32_32x32x16_bf16 v[128:143], v[196:199], v[168:171], v[128:143]
	v_add_f32_e32 v144, v106, v144
	v_add_f32_e32 v144, v107, v144
	v_add_f32_e32 v144, v108, v144
	v_add_f32_e32 v144, v109, v144
	v_cvt_pk_bf16_f32 v156, v104, v105
	v_cvt_pk_bf16_f32 v157, v106, v107
	ds_read_b64_tr_b16 v[104:105], v245 offset:29696
	ds_read_b64_tr_b16 v[106:107], v245 offset:30208
	s_waitcnt lgkmcnt(12)
	v_mfma_f32_32x32x16_bf16 v[112:127], v[192:195], v[168:171], v[112:127]
	v_add_f32_e32 v144, v110, v144
	v_add_f32_e32 v144, v111, v144
	v_add_f32_e32 v144, v80, v144
	v_add_f32_e32 v144, v81, v144
	v_cvt_pk_bf16_f32 v158, v108, v109
	v_cvt_pk_bf16_f32 v159, v110, v111
	ds_read_b64_tr_b16 v[108:109], v245 offset:26624
	ds_read_b64_tr_b16 v[110:111], v245 offset:27136
	s_waitcnt lgkmcnt(13)
	v_mfma_f32_32x32x16_bf16 v[128:143], v[188:191], v[164:167], v[128:143]
	v_add_f32_e32 v144, v82, v144
	v_add_f32_e32 v144, v83, v144
	v_add_f32_e32 v144, v84, v144
	v_add_f32_e32 v144, v85, v144
	v_cvt_pk_bf16_f32 v148, v80, v81
	v_cvt_pk_bf16_f32 v149, v82, v83
	ds_read_b64_tr_b16 v[80:81], v245 offset:30720
	ds_read_b64_tr_b16 v[82:83], v245 offset:31232
	s_waitcnt lgkmcnt(14)
	v_mfma_f32_32x32x16_bf16 v[112:127], v[184:187], v[164:167], v[112:127]
	v_add_f32_e32 v144, v86, v144
	v_add_f32_e32 v144, v87, v144
	v_add_f32_e32 v144, v88, v144
	v_add_f32_e32 v144, v89, v144
	v_cvt_pk_bf16_f32 v150, v84, v85
	v_cvt_pk_bf16_f32 v151, v86, v87
	ds_read_b64_tr_b16 v[84:85], v245 offset:27648
	ds_read_b64_tr_b16 v[86:87], v245 offset:28160
	s_waitcnt lgkmcnt(14)
	v_mfma_f32_32x32x16_bf16 v[128:143], v[180:183], v[152:155], v[128:143]
	v_add_f32_e32 v144, v90, v144
	v_add_f32_e32 v144, v91, v144
	v_add_f32_e32 v144, v92, v144
	v_add_f32_e32 v184, v93, v144
	v_cvt_pk_bf16_f32 v144, v88, v89
	v_cvt_pk_bf16_f32 v145, v90, v91
	ds_read_b64_tr_b16 v[88:89], v245 offset:31744
	ds_read_b64_tr_b16 v[90:91], v245 offset:32256
	v_mfma_f32_32x32x16_bf16 v[112:127], v[176:179], v[152:155], v[112:127]
	v_add_f32_e32 v146, v94, v184
	v_add_f32_e32 v146, v95, v146
	v_add_f32_e32 v180, 0, v146
	v_cvt_pk_bf16_f32 v146, v92, v93
	v_cvt_pk_bf16_f32 v147, v94, v95
	s_add_i32 s4, s35, s71
	s_mov_b32 m0, s4
	s_nop 0
	global_load_lds_dwordx4 v248, s[98:99]
	s_lshl_b32 s4, s36, 1
	s_add_i32 s4, s4, s74
	s_mov_b32 m0, s4
	s_nop 0
	global_load_lds_dwordx4 v250, s[100:101]
	s_addk_i32 s4, 0x2000
	s_mov_b32 m0, s4
	s_nop 0
	global_load_lds_dwordx4 v252, s[100:101]
	v_max_f32_e32 v92, v128, v129
	v_max3_f32 v93, v130, v131, v113
	v_max3_f32 v92, v92, v112, v114
	v_max3_f32 v92, v92, v115, v132
	v_max3_f32 v93, v93, v134, v135
	v_max3_f32 v92, v92, v133, v116
	v_max3_f32 v93, v93, v118, v119
	v_max3_f32 v92, v92, v117, v136
	v_max3_f32 v93, v93, v138, v139
	v_max3_f32 v92, v92, v137, v120
	v_max3_f32 v93, v93, v122, v123
	v_max3_f32 v92, v92, v121, v140
	v_max3_f32 v93, v93, v142, v143
	v_max3_f32 v92, v92, v141, v124
	v_max3_f32 v93, v93, v126, v127
	v_max3_f32 v92, v92, v125, v93
	v_mov_b32_e32 v93, v92
	s_nop 1
	v_permlane32_swap_b32_e32 v92, v93
	v_max_f32_e32 v92, v92, v93
	v_cmp_lt_f32_e32 vcc, s41, v92
	s_cmp_lg_u64 vcc, 0
	v_add_f32_e32 v233, v243, v180
	s_cselect_b64 s[10:11], -1, 0
	s_cbranch_vccnz .LBB0_1367

.LBB0_1362:
	s_add_i32 s4, s36, 0x2000
	s_cmpk_lg_i32 s36, 0x4000
	s_cselect_b32 s75, s4, 0
	s_lshl_b32 s4, s35, 1
	v_add_u32_e32 v209, s4, v240
	ds_read_b64_tr_b16 v[196:197], v209 offset:24576
	ds_read_b64_tr_b16 v[198:199], v209 offset:25088
	s_waitcnt lgkmcnt(9)
	v_mfma_f32_32x32x16_bf16 v[96:111], v[80:83], v[172:175], v[64:79]
	v_add_f32_e32 v84, v128, v129
	v_add_f32_e32 v84, v130, v84
	v_add_f32_e32 v84, v131, v84
	v_add_f32_e32 v84, v132, v84
	v_add_f32_e32 v84, v133, v84
	v_cvt_pk_bf16_f32 v160, v128, v129
	v_cvt_pk_bf16_f32 v161, v130, v131
	ds_read_b64_tr_b16 v[128:129], v209 offset:28672
	ds_read_b64_tr_b16 v[130:131], v209 offset:29184
	v_add_f32_e32 v80, v134, v84
	v_add_f32_e32 v80, v135, v80
	v_add_f32_e32 v80, v136, v80
	v_add_f32_e32 v144, v137, v80
	s_waitcnt lgkmcnt(10)
	v_mfma_f32_32x32x16_bf16 v[80:95], v[204:207], v[172:175], v[64:79]
	v_cvt_pk_bf16_f32 v162, v132, v133
	v_cvt_pk_bf16_f32 v163, v134, v135
	ds_read_b64_tr_b16 v[132:133], v209 offset:25600
	ds_read_b64_tr_b16 v[134:135], v209 offset:26112
	s_waitcnt lgkmcnt(11)
	v_mfma_f32_32x32x16_bf16 v[96:111], v[200:203], v[168:171], v[96:111]
	v_add_f32_e32 v144, v138, v144
	v_add_f32_e32 v144, v139, v144
	v_add_f32_e32 v144, v140, v144
	v_add_f32_e32 v144, v141, v144
	v_cvt_pk_bf16_f32 v156, v136, v137
	v_cvt_pk_bf16_f32 v157, v138, v139
	ds_read_b64_tr_b16 v[136:137], v209 offset:29696
	ds_read_b64_tr_b16 v[138:139], v209 offset:30208
	s_waitcnt lgkmcnt(12)
	v_mfma_f32_32x32x16_bf16 v[80:95], v[192:195], v[168:171], v[80:95]
	v_add_f32_e32 v144, v142, v144
	v_add_f32_e32 v144, v143, v144
	v_add_f32_e32 v144, v112, v144
	v_add_f32_e32 v144, v113, v144
	v_cvt_pk_bf16_f32 v158, v140, v141
	v_cvt_pk_bf16_f32 v159, v142, v143
	ds_read_b64_tr_b16 v[140:141], v209 offset:26624
	ds_read_b64_tr_b16 v[142:143], v209 offset:27136
	s_waitcnt lgkmcnt(13)
	v_mfma_f32_32x32x16_bf16 v[96:111], v[188:191], v[164:167], v[96:111]
	v_add_f32_e32 v144, v114, v144
	v_add_f32_e32 v144, v115, v144
	v_add_f32_e32 v144, v116, v144
	v_add_f32_e32 v144, v117, v144
	v_cvt_pk_bf16_f32 v148, v112, v113
	v_cvt_pk_bf16_f32 v149, v114, v115
	ds_read_b64_tr_b16 v[112:113], v209 offset:30720
	ds_read_b64_tr_b16 v[114:115], v209 offset:31232
	s_waitcnt lgkmcnt(14)
	v_mfma_f32_32x32x16_bf16 v[80:95], v[184:187], v[164:167], v[80:95]
	v_add_f32_e32 v144, v118, v144
	v_add_f32_e32 v144, v119, v144
	v_add_f32_e32 v144, v120, v144
	v_add_f32_e32 v144, v121, v144
	v_cvt_pk_bf16_f32 v150, v116, v117
	v_cvt_pk_bf16_f32 v151, v118, v119
	ds_read_b64_tr_b16 v[116:117], v209 offset:27648
	ds_read_b64_tr_b16 v[118:119], v209 offset:28160
	s_waitcnt lgkmcnt(14)
	v_mfma_f32_32x32x16_bf16 v[96:111], v[180:183], v[152:155], v[96:111]
	v_add_f32_e32 v144, v122, v144
	v_add_f32_e32 v144, v123, v144
	v_add_f32_e32 v144, v124, v144
	v_add_f32_e32 v184, v125, v144
	v_cvt_pk_bf16_f32 v144, v120, v121
	v_cvt_pk_bf16_f32 v145, v122, v123
	ds_read_b64_tr_b16 v[120:121], v209 offset:31744
	ds_read_b64_tr_b16 v[122:123], v209 offset:32256
	v_mfma_f32_32x32x16_bf16 v[80:95], v[176:179], v[152:155], v[80:95]
	v_add_f32_e32 v146, v126, v184
	v_add_f32_e32 v146, v127, v146
	v_add_f32_e32 v180, 0, v146
	v_cvt_pk_bf16_f32 v146, v124, v125
	v_cvt_pk_bf16_f32 v147, v126, v127
	v_max_f32_e32 v124, v96, v97
	s_nop 3
	s_nop 1
	v_max3_f32 v125, v98, v99, v81
	v_max3_f32 v124, v124, v80, v82
	v_max3_f32 v124, v124, v83, v100
	v_max3_f32 v125, v125, v102, v103
	v_max3_f32 v124, v124, v101, v84
	v_max3_f32 v125, v125, v86, v87
	v_max3_f32 v124, v124, v85, v104
	v_max3_f32 v125, v125, v106, v107
	v_max3_f32 v124, v124, v105, v88
	v_max3_f32 v125, v125, v90, v91
	v_max3_f32 v124, v124, v89, v108
	v_max3_f32 v125, v125, v110, v111
	v_max3_f32 v124, v124, v109, v92
	v_max3_f32 v125, v125, v94, v95
	v_max3_f32 v124, v124, v93, v125
	v_mov_b32_e32 v125, v124
	s_add_i32 s4, s36, s71
	s_nop 0
	v_permlane32_swap_b32_e32 v124, v125
	s_mov_b32 m0, s4
	s_nop 0
	global_load_lds_dwordx4 v249, s[98:99]
	s_lshl_b32 s4, s75, 1
	s_add_i32 s4, s4, s74
	s_mov_b32 m0, s4
	s_nop 0
	global_load_lds_dwordx4 v251, s[100:101]
	v_max_f32_e32 v124, v124, v125
	s_addk_i32 s4, 0x2000
	s_mov_b32 m0, s4
	s_nop 0
	global_load_lds_dwordx4 v253, s[100:101]
	v_cmp_lt_f32_e32 vcc, s41, v124
	s_cmp_lg_u64 vcc, 0
	v_add_f32_e32 v243, v233, v180
	s_cselect_b64 s[10:11], -1, 0
	s_cbranch_vccnz .LBB0_1370

.LBB0_1365:
	s_add_i32 s34, s34, 2
	s_add_i32 s4, s75, 0x2000
	s_cmpk_lg_i32 s75, 0x4000
	s_cselect_b32 s76, s4, 0
	s_add_u32 s98, s98, s16
	s_addc_u32 s99, s99, s17
	s_add_u32 s100, s100, s16
	s_addc_u32 s101, s101, s17
	s_cmp_ge_i32 s34, s70
	s_cbranch_scc1 .LBB0_1424
	s_mov_b32 s4, s36
	s_mov_b32 s35, s75
	s_mov_b32 s36, s76
	s_branch .LBB0_1359

	.amdhsa_kernel _Z8fwd_mega4Args
		.amdhsa_group_segment_fixed_size 0
		.amdhsa_private_segment_fixed_size 0
		.amdhsa_kernarg_size 488
		.amdhsa_user_sgpr_count 2
		.amdhsa_user_sgpr_dispatch_ptr 0
		.amdhsa_user_sgpr_queue_ptr 0
		.amdhsa_user_sgpr_kernarg_segment_ptr 1
		.amdhsa_user_sgpr_dispatch_id 0
		.amdhsa_user_sgpr_kernarg_preload_length 0
		.amdhsa_user_sgpr_kernarg_preload_offset 0
		.amdhsa_user_sgpr_private_segment_size 0
		.amdhsa_uses_dynamic_stack 0
		.amdhsa_enable_private_segment 0
		.amdhsa_system_sgpr_workgroup_id_x 1
		.amdhsa_system_sgpr_workgroup_id_y 0
		.amdhsa_system_sgpr_workgroup_id_z 0
		.amdhsa_system_sgpr_workgroup_info 0
		.amdhsa_system_vgpr_workitem_id 2
		.amdhsa_next_free_vgpr 256
		.amdhsa_next_free_sgpr 102
		.amdhsa_accum_offset 256
		.amdhsa_reserve_vcc 1
		.amdhsa_float_round_mode_32 0
		.amdhsa_float_round_mode_16_64 0
		.amdhsa_float_denorm_mode_32 3
		.amdhsa_float_denorm_mode_16_64 3
		.amdhsa_dx10_clamp 1
		.amdhsa_ieee_mode 1
		.amdhsa_fp16_overflow 0
		.amdhsa_tg_split 0
		.amdhsa_exception_fp_ieee_invalid_op 0
		.amdhsa_exception_fp_denorm_src 0
		.amdhsa_exception_fp_ieee_div_zero 0
		.amdhsa_exception_fp_ieee_overflow 0
		.amdhsa_exception_fp_ieee_underflow 0
		.amdhsa_exception_fp_ieee_inexact 0
		.amdhsa_exception_int_div_zero 0
	.end_amdhsa_kernel

.Lfunc_end0:
	.size	_Z8fwd_mega4Args, .Lfunc_end0-_Z8fwd_mega4Args
	.set _Z8fwd_mega4Args.num_vgpr, 256
	.set _Z8fwd_mega4Args.num_agpr, 0
	.set _Z8fwd_mega4Args.numbered_sgpr, 102
	.set _Z8fwd_mega4Args.num_named_barrier, 0
	.set _Z8fwd_mega4Args.private_seg_size, 0
	.set _Z8fwd_mega4Args.uses_vcc, 1
	.set _Z8fwd_mega4Args.uses_flat_scratch, 0
	.set _Z8fwd_mega4Args.has_dyn_sized_stack, 0
	.set _Z8fwd_mega4Args.has_recursion, 0
	.set _Z8fwd_mega4Args.has_indirect_call, 0

amdhsa.kernels:
  - .agpr_count:     0
    .args:
      - .offset:         0
        .size:           232
        .value_kind:     by_value
      - .offset:         232
        .size:           4
        .value_kind:     hidden_block_count_x
      - .offset:         236
        .size:           4
        .value_kind:     hidden_block_count_y
      - .offset:         240
        .size:           4
        .value_kind:     hidden_block_count_z
      - .offset:         244
        .size:           2
        .value_kind:     hidden_group_size_x
      - .offset:         246
        .size:           2
        .value_kind:     hidden_group_size_y
      - .offset:         248
        .size:           2
        .value_kind:     hidden_group_size_z
      - .offset:         250
        .size:           2
        .value_kind:     hidden_remainder_x
      - .offset:         252
        .size:           2
        .value_kind:     hidden_remainder_y
      - .offset:         254
        .size:           2
        .value_kind:     hidden_remainder_z
      - .offset:         272
        .size:           8
        .value_kind:     hidden_global_offset_x
      - .offset:         280
        .size:           8
        .value_kind:     hidden_global_offset_y
      - .offset:         288
        .size:           8
        .value_kind:     hidden_global_offset_z
      - .offset:         296
        .size:           2
        .value_kind:     hidden_grid_dims
      - .offset:         320
        .size:           8
        .value_kind:     hidden_multigrid_sync_arg
      - .offset:         352
        .size:           4
        .value_kind:     hidden_dynamic_lds_size
    .group_segment_fixed_size: 0
    .kernarg_segment_align: 8
    .kernarg_segment_size: 488
    .language:       OpenCL C
    .language_version:
      - 2
      - 0
    .max_flat_workgroup_size: 512
    .name:           _Z8fwd_mega4Args
    .private_segment_fixed_size: 0
    .sgpr_count:     108
    .sgpr_spill_count: 72
    .symbol:         _Z8fwd_mega4Args.kd
    .uniform_work_group_size: 1
    .uses_dynamic_stack: false
    .vgpr_count:     256
    .vgpr_spill_count: 0
    .wavefront_size: 64
